# attention: V tile staged row-major with 2 ds_write_b128 (was 16 ds_write_b16) and PV fragments via ds_read_b64_tr_b16, pipelined; scan producer waves at raised priority
# speedup vs baseline: 1.0732x; 1.0173x over previous
.LBB0_305:
	s_and_saveexec_b64 s[58:59], s[38:39]
	s_xor_b64 s[82:83], exec, s[58:59]
	s_cbranch_execz .LBB0_364
	s_cmp_ge_i32 s97, s96
	s_cbranch_scc1 .LBB0_364
	s_setprio 2
	v_lshl_add_u32 v18, s97, 6, v151
	v_sub_u32_e32 v19, 0x7ff, v18
	v_cndmask_b32_e64 v22, v19, v18, s[56:57]
	v_ashrrev_i32_e32 v23, 31, v22
	v_lshl_add_u64 v[18:19], s[22:23], 0, v[22:23]
	v_mov_b64_e32 v[20:21], s[30:31]
	v_mad_u64_u32 v[44:45], s[58:59], v18, s89, v[20:21]
	v_mad_i32_i24 v45, v19, s89, v45
	s_mov_b64 s[58:59], 0x1400
	v_lshl_add_u64 v[20:21], v[44:45], 0, s[58:59]
	v_lshlrev_b32_e32 v42, 1, v148
	v_mov_b32_e32 v43, v34
	v_lshl_add_u64 v[24:25], v[20:21], 0, v[42:43]
	global_load_dwordx4 v[84:87], v[24:25], off
	v_cmp_lt_i32_e64 s[58:59], 0, v22
	v_mov_b32_e32 v92, 0
	v_mov_b32_e32 v96, 0
	v_mov_b32_e32 v97, 0
	v_mov_b32_e32 v98, 0
	v_mov_b32_e32 v99, 0
	s_and_saveexec_b64 s[60:61], s[58:59]
	s_cbranch_execz .LBB0_309
	v_lshl_add_u64 v[24:25], v[44:45], 0, v[42:43]
	global_load_dwordx4 v[96:99], v[24:25], off offset:-2816

.LBB0_369:
	s_setprio 0
	v_readlane_b32 s96, v244, 9
	v_readlane_b32 s97, v244, 10

.LBB0_668:
	s_andn2_b64 vcc, exec, s[22:23]
	s_cbranch_vccnz .LBB0_696
	s_mov_b64 s[22:23], s[96:97]
	v_mov_b32_e32 v5, v1
	s_load_dwordx2 s[30:31], s[22:23], 0xf8
	s_load_dwordx4 s[40:43], s[22:23], 0x30
	v_readlane_b32 s38, v244, 13
	v_and_b32_e32 v148, 63, v5
	v_readlane_b32 s39, v244, 14
	v_lshlrev_b32_e32 v2, 2, v148
	s_waitcnt lgkmcnt(0)
	s_add_u32 s38, s40, s38
	s_addc_u32 s39, s41, s39
	s_load_dwordx2 s[22:23], s[22:23], 0x40
	global_load_dword v7, v2, s[38:39]
	global_load_dword v10, v2, s[38:39] offset:256
	global_load_dword v11, v2, s[38:39] offset:512
	global_load_dword v12, v2, s[38:39] offset:768
	v_cmp_lt_i32_e32 vcc, v219, v218
	v_cvt_f32_i32_e32 v4, s28
	s_movk_i32 s28, 0x101
	v_cndmask_b32_e32 v2, v217, v219, vcc
	v_cmp_lt_i32_e32 vcc, v220, v218
	v_cmp_gt_i32_e64 s[38:39], s28, v5
	s_movk_i32 s28, 0x80
	v_cndmask_b32_e32 v6, v217, v220, vcc
	v_cmp_lt_i32_e32 vcc, v221, v218
	v_lshlrev_b32_e32 v16, 2, v6
	v_add_u32_e32 v6, 0xffffff80, v5
	v_cndmask_b32_e32 v8, v217, v221, vcc
	v_cmp_lt_i32_e32 vcc, v222, v218
	v_lshlrev_b32_e32 v17, 2, v8
	v_bfe_u32 v8, v5, 4, 2
	v_cndmask_b32_e32 v9, v217, v222, vcc
	v_cmp_lt_i32_e32 vcc, v223, v218
	v_lshlrev_b32_e32 v18, 2, v9
	v_sub_u32_e32 v9, 0x80, v5
	v_cndmask_b32_e32 v13, v217, v223, vcc
	v_cmp_lt_i32_e32 vcc, v224, v218
	v_max_i32_e32 v20, v6, v9
	v_lshlrev_b32_e32 v35, 2, v13
	v_cndmask_b32_e32 v14, v217, v224, vcc
	v_cmp_lt_i32_e32 vcc, s28, v5
	v_and_b32_e32 v151, 15, v5
	v_ashrrev_i32_e32 v150, 4, v5
	v_cndmask_b32_e64 v13, 0, 16, vcc
	v_mul_f32_e32 v19, 0xbe99999a, v4
	v_cmp_gt_u32_e32 vcc, s90, v20
	v_lshlrev_b32_e32 v4, 3, v8
	v_bitop3_b32 v9, v150, v5, 7 bitop3:0x78
	v_lshlrev_b32_e32 v156, 2, v8
	v_bitop3_b32 v157, v8, v5, 15 bitop3:0x78
	v_bitop3_b32 v175, v8, v151, 4 bitop3:0x36
	v_lshl_add_u32 v176, v8, 10, 0
	v_mul_f32_e32 v8, 0x3fb8aa3b, v19
	v_cndmask_b32_e64 v19, 15, 14, vcc
	v_cmp_lt_u32_e32 vcc, 63, v20
	v_lshlrev_b32_e32 v21, 10, v151
	v_lshlrev_b32_e32 v9, 4, v9
	v_min_u32_e32 v23, 8, v20
	v_exp_f32_e32 v24, v8
	v_cndmask_b32_e32 v8, 13, v19, vcc
	v_cmp_gt_u32_e32 vcc, 12, v20
	v_lshlrev_b32_e32 v15, 2, v2
	v_add3_u32 v178, 0, v21, v9
	v_cndmask_b32_e32 v9, 9, v23, vcc
	v_lshlrev_b32_e32 v149, 2, v14
	v_ashrrev_i32_e32 v14, 2, v5
	v_and_b32_e32 v154, -16, v14
	v_cmp_lt_u32_e32 vcc, 45, v20
	v_ashrrev_i32_e32 v155, 31, v154
	s_mov_b64 s[28:29], 0x64f8c10
	v_cndmask_b32_e32 v19, 12, v8, vcc
	v_cmp_gt_u32_e32 vcc, 16, v20
	v_mov_b32_e32 v3, v34
	v_and_b32_e32 v2, 48, v5
	v_cndmask_b32_e32 v21, 10, v9, vcc
	v_lshl_add_u64 v[8:9], v[154:155], 1, s[30:31]
	v_lshl_add_u64 v[158:159], v[8:9], 0, s[28:29]
	v_cmp_lt_u32_e32 vcc, 31, v20
	s_add_u32 s28, s30, 0x6400000
	s_addc_u32 s29, s31, 0
	v_cndmask_b32_e32 v19, 11, v19, vcc
	v_cmp_gt_u32_e32 vcc, 23, v20
	s_add_u32 s2, s42, s2
	s_addc_u32 s3, s43, s3
	v_cndmask_b32_e32 v9, v19, v21, vcc
	v_or_b32_e32 v9, v9, v13
	v_lshlrev_b32_e32 v180, 2, v9
	s_waitcnt vmcnt(4)
	v_lshl_add_u64 v[160:161], s[2:3], 0, v[2:3]
	s_load_dword s24, s[72:73], 0x10
	v_lshl_add_u32 v152, v148, 1, 0
	v_lshlrev_b32_e32 v6, 3, v151
	v_mul_lo_u32 v22, v154, s92
	s_mov_b32 s33, 0
	s_waitcnt vmcnt(2)
	v_mul_f32_e32 v23, v7, v10
	ds_bpermute_b32 v23, v15, v23
	s_waitcnt vmcnt(0)
	v_mul_f32_e32 v25, v11, v12
	ds_bpermute_b32 v15, v15, v25
	s_waitcnt lgkmcnt(0)
	s_lshr_b32 s24, s24, 16
	s_cmp_lg_u32 s24, 0
	v_fmac_f32_e32 v23, v7, v10
	ds_bpermute_b32 v7, v16, v23
	v_fmac_f32_e32 v15, v11, v12
	ds_bpermute_b32 v8, v16, v15
	s_cselect_b64 s[2:3], -1, 0
	s_cmp_lg_u64 s[2:3], 0
	s_waitcnt lgkmcnt(1)
	v_add_f32_e32 v7, v23, v7
	ds_bpermute_b32 v11, v17, v7
	s_waitcnt lgkmcnt(1)
	v_add_f32_e32 v8, v15, v8
	ds_bpermute_b32 v12, v17, v8
	s_addc_u32 s2, s74, 0
	s_lshr_b32 s42, s2, 3
	s_waitcnt lgkmcnt(1)
	v_add_f32_e32 v7, v7, v11
	ds_bpermute_b32 v11, v18, v7
	s_waitcnt lgkmcnt(1)
	v_add_f32_e32 v8, v8, v12
	ds_bpermute_b32 v12, v18, v8
	v_fmamk_f32 v10, v24, 0xbf19999a, v215
	s_mul_i32 s3, s35, s42
	s_waitcnt lgkmcnt(1)
	v_add_f32_e32 v7, v7, v11
	ds_bpermute_b32 v9, v35, v7
	s_waitcnt lgkmcnt(1)
	v_add_f32_e32 v8, v8, v12
	ds_bpermute_b32 v11, v35, v8
	s_add_i32 s43, s37, s3
	s_and_b32 s44, s2, -8
	s_waitcnt lgkmcnt(1)
	v_add_f32_e32 v2, v7, v9
	ds_bpermute_b32 v7, v149, v2
	s_waitcnt lgkmcnt(1)
	v_add_f32_e32 v3, v8, v11
	ds_bpermute_b32 v8, v149, v3
	v_lshl_add_u32 v153, v5, 2, s91
	v_add_u32_e32 v177, 0, v4
	s_waitcnt lgkmcnt(1)
	v_add_f32_e32 v2, v2, v7
	v_mul_f32_e32 v2, 0x3fb8aa3b, v2
	s_waitcnt lgkmcnt(0)
	v_add_f32_e32 v3, v3, v8
	v_mul_f32_e32 v3, 0x3fb8aa3b, v3
	v_exp_f32_e32 v2, v2
	v_exp_f32_e32 v3, v3
	v_sub_f32_e32 v179, 1.0, v10
	v_bfi_b32 v182, -16, v14, v5
	s_lshl_b32 s45, s43, 7
	v_sub_f32_e32 v2, v2, v3
	v_add_f32_e32 v181, v10, v2
	v_mad_i64_i32 v[2:3], s[2:3], v150, s89, 0
	v_lshl_or_b32 v2, v151, 4, v2
	v_lshl_add_u64 v[2:3], s[30:31], 0, v[2:3]
	s_mov_b64 s[2:3], 0x6536800
	s_lshl_b32 s46, s42, 10
	v_lshl_add_u64 v[162:163], v[2:3], 0, s[2:3]
	s_lshl_b32 s47, s43, 5
	s_lshl_b32 s48, s42, 8
	v_subrev_u32_e32 v183, 63, v154
	v_sub_u32_e32 v184, 0, v154
	v_lshlrev_b32_e32 v164, 1, v4
	v_lshlrev_b32_e32 v166, 1, v6
	v_add_u32_e32 v185, v152, v22
	v_mul_u32_u24_e32 v226, 0x120, v148
	v_lshl_add_u32 v226, v154, 1, v226
	v_lshrrev_b32_e32 v227, 2, v148
	v_mul_u32_u24_e32 v227, 0x120, v227
	v_and_b32_e32 v228, 3, v148
	v_lshl_add_u32 v227, v228, 3, v227
	s_branch .LBB0_671

.LBB0_675:
	s_or_b64 exec, exec, s[2:3]
	s_lshr_b32 s2, s24, 4
	s_lshl_b32 s3, s24, 5
	s_lshl_b32 s2, s2, 2
	s_and_b32 s31, s3, 0x7800
	s_or_b32 s3, s2, 0xf0
	v_mov_b32_e32 v2, s3
	s_or_b32 s2, s2, 0x1f0
	global_load_dword v186, v2, s[22:23]
	v_mov_b32_e32 v2, s2
	s_lshl_b32 s2, s24, 7
	s_and_b32 s2, s2, 0x780
	v_add_u32_e32 v188, s2, v154
	global_load_dword v187, v2, s[22:23]
	v_or_b32_e32 v2, v188, v151
	v_add_u32_e32 v2, s31, v2
	v_mov_b64_e32 v[4:5], s[28:29]
	v_mad_i64_i32 v[2:3], s[2:3], v2, s89, v[4:5]
	s_lshl_b32 s24, s30, 8
	v_lshl_add_u64 v[168:169], v[2:3], 0, s[24:25]
	v_mov_b32_e32 v165, v34
	v_lshl_add_u64 v[2:3], v[168:169], 0, v[164:165]
	global_load_dwordx4 v[36:39], v[2:3], off offset:1024
	global_load_dwordx4 v[40:43], v[2:3], off offset:1088
	global_load_dwordx4 v[44:47], v[2:3], off offset:1152
	global_load_dwordx4 v[48:51], v[2:3], off offset:1216
	v_add_u32_e32 v2, s31, v150
	v_mad_i64_i32 v[2:3], s[2:3], v2, s89, v[4:5]
	v_lshl_add_u64 v[2:3], v[2:3], 0, s[24:25]
	v_mov_b32_e32 v167, v34
	v_lshl_add_u64 v[20:21], v[2:3], 0, v[166:167]
	v_or_b32_e32 v2, s31, v148
	v_mad_u64_u32 v[4:5], s[2:3], v2, s89, v[4:5]
	s_mov_b32 s2, 0x3e000
	s_nop 0
	v_add_co_u32_e32 v8, vcc, s2, v20
	v_lshl_add_u64 v[4:5], v[4:5], 0, s[24:25]
	s_nop 0
	v_addc_co_u32_e32 v9, vcc, 0, v21, vcc
	v_lshl_add_u64 v[22:23], v[154:155], 1, v[4:5]
	global_load_dwordx4 v[4:7], v[20:21], off offset:2048
	s_nop 0
	global_load_dwordx4 v[8:11], v[8:9], off offset:2048
	s_nop 0
	global_load_dwordx4 v[12:15], v[22:23], off offset:3088
	global_load_dwordx4 v[16:19], v[22:23], off offset:3072
	s_mov_b32 s2, 0x7c000
	s_mov_b32 s30, 32
	s_waitcnt vmcnt(3)
	ds_write_b128 v178, v[4:7]
	s_waitcnt vmcnt(2)
	ds_write_b128 v178, v[8:11] offset:512
	s_waitcnt vmcnt(0)
	ds_write_b128 v226, v[16:19] offset:34816
	ds_write_b128 v226, v[12:15] offset:34832
	v_add_co_u32_e32 v4, vcc, s2, v20
	s_nop 1
	v_addc_co_u32_e32 v5, vcc, 0, v21, vcc
	global_load_dwordx4 v[72:75], v[4:5], off offset:2048
	v_add_co_u32_e32 v4, vcc, 0xba000, v20
	s_nop 1
	v_addc_co_u32_e32 v5, vcc, 0, v21, vcc
	global_load_dwordx4 v[80:83], v[4:5], off offset:2048
	v_add_co_u32_e32 v4, vcc, 0x7c000, v22
	s_nop 1
	v_addc_co_u32_e32 v5, vcc, 0, v23, vcc
	global_load_dwordx4 v[84:87], v[4:5], off offset:3072
	global_load_dwordx4 v[92:95], v[4:5], off offset:3088
	s_waitcnt lgkmcnt(0)
	s_barrier
	s_cmp_lt_i32 s30, 1
	s_cbranch_scc1 .LBB0_690
	s_lshl_b32 s2, s43, 4
	s_and_b32 s24, s2, 0x300
	s_bfe_u32 s2, s47, 0x4000b
	v_mul_hi_u32_u24_e32 v3, 0x1f00, v2
	v_mul_u32_u24_e32 v2, 0x1f00, v2
	s_and_b32 s31, s45, 0x780
	s_mul_i32 s2, s2, 0xf80000
	v_add_u32_e32 v4, s31, v182
	s_or_b32 s2, s2, s24
	s_mov_b32 s3, s25
	v_lshl_add_u64 v[2:3], v[2:3], 0, s[24:25]
	v_mov_b32_e32 v192, 0
	v_sub_u32_e32 v165, v156, v4
	v_lshl_add_u64 v[170:171], v[162:163], 0, s[2:3]
	v_add_u32_e32 v167, s31, v183
	v_subrev_u32_e32 v189, s31, v184
	v_lshl_add_u64 v[172:173], v[158:159], 0, v[2:3]
	s_mov_b32 s24, 0
	s_sub_i32 s31, 0, s30
	v_mov_b32_e32 v193, 0xf149f2ca
	s_mov_b32 s49, 2
	v_mov_b32_e32 v191, 0xf149f2ca
	v_mov_b32_e32 v190, 0
	v_mov_b32_e32 v112, 0
	v_mov_b32_e32 v113, v192
	v_mov_b32_e32 v114, v192
	v_mov_b32_e32 v115, v192
	v_mov_b32_e32 v116, 0
	v_mov_b32_e32 v117, v192
	v_mov_b32_e32 v118, v192
	v_mov_b32_e32 v119, v192
	v_mov_b32_e32 v120, 0
	v_mov_b32_e32 v121, v192
	v_mov_b32_e32 v122, v192
	v_mov_b32_e32 v123, v192
	v_mov_b32_e32 v124, 0
	v_mov_b32_e32 v125, v192
	v_mov_b32_e32 v126, v192
	v_mov_b32_e32 v127, v192
	v_mov_b32_e32 v96, 0
	v_mov_b32_e32 v97, v192
	v_mov_b32_e32 v98, v192
	v_mov_b32_e32 v99, v192
	v_mov_b32_e32 v52, 0
	v_mov_b32_e32 v53, v192
	v_mov_b32_e32 v54, v192
	v_mov_b32_e32 v55, v192
	v_mov_b32_e32 v56, 0
	v_mov_b32_e32 v57, v192
	v_mov_b32_e32 v58, v192
	v_mov_b32_e32 v59, v192
	v_mov_b32_e32 v60, 0
	v_mov_b32_e32 v61, v192
	v_mov_b32_e32 v62, v192
	v_mov_b32_e32 v63, v192
	v_mov_b32_e32 v64, 0
	v_mov_b32_e32 v65, v192
	v_mov_b32_e32 v66, v192
	v_mov_b32_e32 v67, v192
	v_mov_b32_e32 v68, 0
	v_mov_b32_e32 v69, v192
	v_mov_b32_e32 v70, v192
	v_mov_b32_e32 v71, v192
	v_mov_b32_e32 v76, 0
	v_mov_b32_e32 v77, v192
	v_mov_b32_e32 v78, v192
	v_mov_b32_e32 v79, v192
	v_mov_b32_e32 v88, 0
	v_mov_b32_e32 v89, v192
	v_mov_b32_e32 v90, v192
	v_mov_b32_e32 v91, v192
	v_mov_b32_e32 v108, 0
	v_mov_b32_e32 v109, v192
	v_mov_b32_e32 v110, v192
	v_mov_b32_e32 v111, v192
	v_mov_b32_e32 v104, 0
	v_mov_b32_e32 v105, v192
	v_mov_b32_e32 v106, v192
	v_mov_b32_e32 v107, v192
	v_mov_b32_e32 v100, 0
	v_mov_b32_e32 v101, v192
	v_mov_b32_e32 v102, v192
	v_mov_b32_e32 v103, v192
	v_mov_b32_e32 v128, 0
	v_mov_b32_e32 v129, v192
	v_mov_b32_e32 v130, v192
	v_mov_b32_e32 v131, v192

.LBB0_679:
	s_or_saveexec_b64 s[2:3], s[2:3]
	v_cndmask_b32_e64 v132, v186, v187, s[40:41]
	v_mul_f32_e32 v174, 0x3fb8aa3b, v132
	s_xor_b64 exec, exec, s[2:3]
	v_fma_f32 v16, v32, s36, v174
	v_fma_f32 v17, v33, s36, v174
	v_fma_f32 v12, v28, s36, v174
	v_fma_f32 v13, v29, s36, v174
	v_fma_f32 v8, v24, s36, v174
	v_fma_f32 v9, v25, s36, v174
	v_fma_f32 v4, v20, s36, v174
	v_fma_f32 v5, v21, s36, v174
	v_fma_f32 v14, v30, s36, v174
	v_fma_f32 v15, v31, s36, v174
	v_fma_f32 v10, v26, s36, v174
	v_fma_f32 v11, v27, s36, v174
	v_fma_f32 v6, v22, s36, v174
	v_fma_f32 v7, v23, s36, v174
	v_fma_f32 v2, v18, s36, v174
	v_fma_f32 v3, v19, s36, v174
	s_or_b64 exec, exec, s[2:3]
	v_max_f32_e32 v18, v3, v3
	v_max_f32_e32 v19, v2, v2
	v_max_f32_e32 v18, v19, v18
	v_max3_f32 v18, v18, v4, v5
	v_max3_f32 v18, v18, v6, v7
	v_max3_f32 v18, v18, v8, v9
	v_max3_f32 v18, v18, v10, v11
	v_max3_f32 v18, v18, v12, v13
	v_max3_f32 v18, v18, v14, v15
	v_max3_f32 v18, v18, v16, v17
	ds_bpermute_b32 v19, v35, v18
	s_waitcnt lgkmcnt(0)
	v_max_f32_e32 v19, v19, v19
	v_max_f32_e32 v194, v18, v19
	ds_bpermute_b32 v195, v149, v194
	ds_read_b128 v[18:21], v145 offset:8192
	ds_read_b128 v[22:25], v144 offset:12288
	ds_read_b128 v[26:29], v145 offset:8448
	ds_read_b128 v[30:33], v144 offset:12544
	ds_read_b128 v[246:249], v145 offset:8704
	ds_read_b128 v[250:253], v144 offset:12800
	s_waitcnt lgkmcnt(5)
	v_mfma_f32_16x16x32_f16 v[132:135], v[18:21], v[44:47], 0
	s_waitcnt lgkmcnt(4)
	v_mfma_f32_16x16x32_f16 v[132:135], v[22:25], v[48:51], v[132:135]
	ds_read_b128 v[18:21], v145 offset:8960
	ds_read_b128 v[22:25], v144 offset:13056
	s_waitcnt lgkmcnt(5)
	v_mfma_f32_16x16x32_f16 v[136:139], v[26:29], v[44:47], 0
	s_waitcnt lgkmcnt(4)
	v_mfma_f32_16x16x32_f16 v[136:139], v[30:33], v[48:51], v[136:139]
	s_waitcnt lgkmcnt(3)
	v_mfma_f32_16x16x32_f16 v[140:143], v[246:249], v[44:47], 0
	s_waitcnt lgkmcnt(2)
	v_mfma_f32_16x16x32_f16 v[140:143], v[250:253], v[48:51], v[140:143]
	s_waitcnt lgkmcnt(1)
	v_mfma_f32_16x16x32_f16 v[144:147], v[18:21], v[44:47], 0
	s_waitcnt lgkmcnt(0)
	v_mfma_f32_16x16x32_f16 v[144:147], v[22:25], v[48:51], v[144:147]
	s_and_saveexec_b64 s[2:3], vcc
	s_xor_b64 s[2:3], exec, s[2:3]
	s_cbranch_execz .LBB0_683
	s_nop 3
	v_lshl_add_u32 v18, v203, 2, s91
	v_lshl_add_u32 v19, v202, 2, s91
	v_lshl_add_u32 v20, v201, 2, s91
	v_lshl_add_u32 v21, v200, 2, s91
	v_lshl_add_u32 v22, v199, 2, s91
	v_lshl_add_u32 v23, v198, 2, s91
	v_lshl_add_u32 v24, v197, 2, s91
	v_lshl_add_u32 v25, v196, 2, s91
	v_lshl_add_u32 v26, v211, 2, s91
	v_lshl_add_u32 v27, v210, 2, s91
	v_lshl_add_u32 v28, v209, 2, s91
	v_lshl_add_u32 v29, v208, 2, s91
	v_lshl_add_u32 v30, v207, 2, s91
	v_lshl_add_u32 v31, v206, 2, s91
	v_lshl_add_u32 v32, v205, 2, s91
	v_lshl_add_u32 v33, v204, 2, s91
	ds_read_b32 v18, v18 offset:512
	ds_read_b32 v19, v19 offset:512
	ds_read_b32 v20, v20 offset:512
	ds_read_b32 v21, v21 offset:512
	ds_read_b32 v22, v22 offset:512
	ds_read_b32 v23, v23 offset:512
	ds_read_b32 v24, v24 offset:512
	ds_read_b32 v25, v25 offset:512
	ds_read_b32 v196, v26 offset:512
	ds_read_b32 v197, v27 offset:512
	ds_read_b32 v198, v28 offset:512
	ds_read_b32 v199, v29 offset:512
	ds_read_b32 v200, v30 offset:512
	ds_read_b32 v201, v31 offset:512
	ds_read_b32 v202, v32 offset:512
	ds_read_b32 v203, v33 offset:512
	s_waitcnt lgkmcnt(8)
	v_fma_f32 v32, v146, s36, v24
	v_fma_f32 v33, v147, s36, v25
	v_fma_f32 v30, v144, s36, v22
	v_fma_f32 v31, v145, s36, v23
	v_fma_f32 v28, v142, s36, v20
	v_fma_f32 v29, v143, s36, v21
	v_fma_f32 v26, v140, s36, v18
	v_fma_f32 v27, v141, s36, v19
	s_waitcnt lgkmcnt(0)
	v_fma_f32 v24, v138, s36, v202
	v_fma_f32 v25, v139, s36, v203
	v_fma_f32 v22, v136, s36, v200
	v_fma_f32 v23, v137, s36, v201
	v_fma_f32 v20, v134, s36, v198
	v_fma_f32 v21, v135, s36, v199
	v_fma_f32 v18, v132, s36, v196
	v_fma_f32 v19, v133, s36, v197
.LBB0_683:
	s_andn2_saveexec_b64 s[2:3], s[2:3]
	s_nop 3
	v_fma_f32 v32, v146, s36, v174
	v_fma_f32 v33, v147, s36, v174
	v_fma_f32 v28, v142, s36, v174
	v_fma_f32 v29, v143, s36, v174
	v_fma_f32 v24, v138, s36, v174
	v_fma_f32 v25, v139, s36, v174
	v_fma_f32 v20, v134, s36, v174
	v_fma_f32 v21, v135, s36, v174
	v_fma_f32 v30, v144, s36, v174
	v_fma_f32 v31, v145, s36, v174
	v_fma_f32 v26, v140, s36, v174
	v_fma_f32 v27, v141, s36, v174
	v_fma_f32 v22, v136, s36, v174
	v_fma_f32 v23, v137, s36, v174
	v_fma_f32 v18, v132, s36, v174
	v_fma_f32 v19, v133, s36, v174
	s_or_b64 exec, exec, s[2:3]
	v_max_f32_e32 v132, v19, v19
	v_max_f32_e32 v133, v18, v18
	v_max_f32_e32 v132, v133, v132
	v_max3_f32 v132, v132, v20, v21
	v_max3_f32 v132, v132, v22, v23
	v_max3_f32 v132, v132, v24, v25
	v_max3_f32 v132, v132, v26, v27
	v_max3_f32 v132, v132, v28, v29
	v_max3_f32 v132, v132, v30, v31
	v_max3_f32 v132, v132, v32, v33
	ds_bpermute_b32 v133, v35, v132
	s_waitcnt lgkmcnt(0)
	v_max_f32_e32 v133, v133, v133
	v_max_f32_e32 v132, v132, v133
	ds_bpermute_b32 v133, v149, v132
	s_add_i32 s2, s49, -1
	s_cmp_ge_i32 s2, s30
	s_cbranch_scc1 .LBB0_688
	s_xor_b32 s2, s50, 1
	v_lshl_add_u32 v134, s2, 14, v178
	s_waitcnt vmcnt(3)
	ds_write_b128 v134, v[72:75]
	s_waitcnt vmcnt(2)
	ds_write_b128 v134, v[80:83] offset:512
	s_mul_i32 s3, s2, 0x4800
	v_add_u32_e32 v134, s3, v226
	s_cmp_ge_i32 s49, s30
	s_waitcnt vmcnt(1)
	ds_write_b128 v134, v[84:87] offset:34816
	s_waitcnt vmcnt(0)
	ds_write_b128 v134, v[92:95] offset:34832
	s_cbranch_scc1 .LBB0_688
	v_add_co_u32_e32 v72, vcc, 0xfffc2000, v170
	s_nop 1
	v_addc_co_u32_e32 v73, vcc, -1, v171, vcc
	global_load_dwordx4 v[72:75], v[72:73], off
	s_nop 0
	global_load_dwordx4 v[80:83], v[170:171], off
	global_load_dwordx4 v[84:87], v[172:173], off offset:-16
	global_load_dwordx4 v[92:95], v[172:173], off
.LBB0_688:
	s_waitcnt lgkmcnt(0)
	v_max3_f32 v133, v193, v132, v133
	v_sub_f32_e32 v18, v18, v133
	v_exp_f32_e32 v134, v18
	v_sub_f32_e32 v19, v19, v133
	v_exp_f32_e32 v19, v19
	v_sub_f32_e32 v20, v20, v133
	v_exp_f32_e32 v20, v20
	v_sub_f32_e32 v21, v21, v133
	v_exp_f32_e32 v21, v21
	v_sub_f32_e32 v22, v22, v133
	v_add_f32_e32 v132, 0, v134
	v_exp_f32_e32 v135, v22
	v_sub_f32_e32 v23, v23, v133
	v_add_f32_e32 v22, v19, v132
	v_exp_f32_e32 v136, v23
	v_sub_f32_e32 v23, v24, v133
	v_add_f32_e32 v22, v20, v22
	v_exp_f32_e32 v137, v23
	v_sub_f32_e32 v23, v25, v133
	v_add_f32_e32 v22, v21, v22
	v_exp_f32_e32 v138, v23
	v_sub_f32_e32 v23, v26, v133
	v_add_f32_e32 v22, v135, v22
	v_exp_f32_e32 v139, v23
	v_sub_f32_e32 v23, v27, v133
	v_add_f32_e32 v22, v136, v22
	v_exp_f32_e32 v140, v23
	v_sub_f32_e32 v23, v28, v133
	v_add_f32_e32 v22, v137, v22
	v_exp_f32_e32 v141, v23
	v_sub_f32_e32 v23, v29, v133
	v_add_f32_e32 v22, v138, v22
	v_exp_f32_e32 v142, v23
	v_sub_f32_e32 v23, v30, v133
	v_add_f32_e32 v22, v139, v22
	v_exp_f32_e32 v143, v23
	v_sub_f32_e32 v23, v31, v133
	v_add_f32_e32 v22, v140, v22
	v_exp_f32_e32 v144, v23
	v_sub_f32_e32 v23, v32, v133
	v_sub_f32_e32 v18, v193, v133
	v_add_f32_e32 v22, v141, v22
	v_exp_f32_e32 v145, v23
	v_sub_f32_e32 v23, v33, v133
	v_add_f32_e32 v22, v142, v22
	v_exp_f32_e32 v146, v23
	v_exp_f32_e32 v18, v18
	v_add_f32_e32 v22, v143, v22
	v_add_f32_e32 v22, v144, v22
	v_add_f32_e32 v22, v145, v22
	v_add_f32_e32 v132, v146, v22
	v_mul_f32_e32 v22, v100, v18
	v_mul_f32_e32 v23, v101, v18
	v_cvt_pk_f16_f32 v100, v134, v19
	v_max3_f32 v134, v191, v194, v195
	v_sub_f32_e32 v2, v2, v134
	v_mul_f32_e32 v30, v108, v18
	v_mul_f32_e32 v31, v109, v18
	v_exp_f32_e32 v108, v2
	v_sub_f32_e32 v3, v3, v134
	v_exp_f32_e32 v3, v3
	v_sub_f32_e32 v4, v4, v134
	v_mul_f32_e32 v32, v110, v18
	v_mul_f32_e32 v33, v111, v18
	v_exp_f32_e32 v110, v4
	v_sub_f32_e32 v4, v5, v134
	v_exp_f32_e32 v111, v4
	v_sub_f32_e32 v4, v6, v134
	v_mul_f32_e32 v26, v128, v18
	v_mul_f32_e32 v27, v129, v18
	v_add_f32_e32 v109, 0, v108
	v_exp_f32_e32 v128, v4
	v_sub_f32_e32 v5, v7, v134
	v_add_f32_e32 v4, v3, v109
	v_exp_f32_e32 v109, v5
	v_sub_f32_e32 v5, v8, v134
	v_add_f32_e32 v4, v110, v4
	v_exp_f32_e32 v129, v5
	v_sub_f32_e32 v5, v9, v134
	v_mul_f32_e32 v28, v130, v18
	v_mul_f32_e32 v29, v131, v18
	v_add_f32_e32 v4, v111, v4
	v_exp_f32_e32 v130, v5
	v_sub_f32_e32 v5, v10, v134
	v_add_f32_e32 v4, v128, v4
	v_exp_f32_e32 v131, v5
	v_sub_f32_e32 v5, v11, v134
	v_mul_f32_e32 v24, v102, v18
	v_mul_f32_e32 v25, v103, v18
	v_cvt_pk_f16_f32 v102, v135, v136
	v_add_f32_e32 v4, v109, v4
	v_exp_f32_e32 v135, v5
	v_sub_f32_e32 v5, v12, v134
	v_add_f32_e32 v4, v129, v4
	v_exp_f32_e32 v136, v5
	v_sub_f32_e32 v5, v13, v134
	v_cvt_pk_f16_f32 v103, v137, v138
	v_add_f32_e32 v4, v130, v4
	v_exp_f32_e32 v137, v5
	v_sub_f32_e32 v5, v14, v134
	v_add_f32_e32 v4, v131, v4
	v_exp_f32_e32 v138, v5
	v_sub_f32_e32 v5, v15, v134
	v_fmac_f32_e32 v132, v192, v18
	v_mul_f32_e32 v126, v126, v18
	v_mul_f32_e32 v127, v127, v18
	v_mul_f32_e32 v124, v124, v18
	v_mul_f32_e32 v125, v125, v18
	v_mul_f32_e32 v122, v122, v18
	v_mul_f32_e32 v123, v123, v18
	v_mul_f32_e32 v120, v120, v18
	v_mul_f32_e32 v121, v121, v18
	v_mul_f32_e32 v118, v118, v18
	v_mul_f32_e32 v119, v119, v18
	v_mul_f32_e32 v116, v116, v18
	v_mul_f32_e32 v117, v117, v18
	v_mul_f32_e32 v114, v114, v18
	v_mul_f32_e32 v115, v115, v18
	v_mul_f32_e32 v112, v112, v18
	v_mul_f32_e32 v113, v113, v18
	v_mul_f32_e32 v106, v106, v18
	v_mul_f32_e32 v107, v107, v18
	v_mul_f32_e32 v104, v104, v18
	v_mul_f32_e32 v105, v105, v18
	v_cvt_pk_f16_f32 v18, v139, v140
	v_add_f32_e32 v4, v135, v4
	v_exp_f32_e32 v139, v5
	v_sub_f32_e32 v5, v16, v134
	v_add_f32_e32 v4, v136, v4
	v_exp_f32_e32 v140, v5
	v_sub_f32_e32 v5, v17, v134
	v_sub_f32_e32 v2, v191, v134
	v_add_f32_e32 v4, v137, v4
	v_exp_f32_e32 v17, v5
	v_add_f32_e32 v4, v138, v4
	v_exp_f32_e32 v16, v2
	v_add_f32_e32 v2, v139, v4
	v_add_f32_e32 v2, v140, v2
	v_add_f32_e32 v2, v17, v2
	v_cvt_pk_f16_f32 v101, v20, v21
	v_fmac_f32_e32 v2, v190, v16
	v_mul_f32_e32 v10, v78, v16
	v_mul_f32_e32 v11, v79, v16
	v_mul_f32_e32 v8, v76, v16
	v_mul_f32_e32 v9, v77, v16
	v_mul_f32_e32 v14, v70, v16
	v_mul_f32_e32 v15, v71, v16
	v_mul_f32_e32 v12, v68, v16
	v_mul_f32_e32 v13, v69, v16
	v_mul_f32_e32 v66, v66, v16
	v_mul_f32_e32 v67, v67, v16
	v_mul_f32_e32 v64, v64, v16
	v_mul_f32_e32 v65, v65, v16
	v_mul_f32_e32 v62, v62, v16
	v_mul_f32_e32 v63, v63, v16
	v_mul_f32_e32 v60, v60, v16
	v_mul_f32_e32 v61, v61, v16
	v_mul_f32_e32 v58, v58, v16
	v_mul_f32_e32 v59, v59, v16
	v_mul_f32_e32 v56, v56, v16
	v_mul_f32_e32 v57, v57, v16
	v_mul_f32_e32 v54, v54, v16
	v_mul_f32_e32 v55, v55, v16
	v_mul_f32_e32 v52, v52, v16
	v_mul_f32_e32 v53, v53, v16
	v_mul_f32_e32 v70, v98, v16
	v_mul_f32_e32 v71, v99, v16
	v_mul_f32_e32 v68, v96, v16
	v_mul_f32_e32 v69, v97, v16
	v_cvt_pk_f16_f32 v76, v108, v3
	v_cvt_pk_f16_f32 v77, v110, v111
	v_cvt_pk_f16_f32 v78, v128, v109
	v_cvt_pk_f16_f32 v79, v129, v130
	v_cvt_pk_f16_f32 v96, v131, v135
	v_cvt_pk_f16_f32 v97, v136, v137
	v_cvt_pk_f16_f32 v98, v138, v139
	v_cvt_pk_f16_f32 v99, v140, v17
	v_cvt_pk_f16_f32 v19, v141, v142
	v_cvt_pk_f16_f32 v20, v143, v144
	v_cvt_pk_f16_f32 v21, v145, v146
	v_mul_f32_e32 v6, v90, v16
	v_mul_f32_e32 v7, v91, v16
	v_mul_f32_e32 v4, v88, v16
	v_mul_f32_e32 v5, v89, v16
	s_mul_i32 s2, s50, 0x4800
	v_add_u32_e32 v3, s2, v227
	ds_read_b64_tr_b16 v[140:141], v3 offset:34816
	ds_read_b64_tr_b16 v[142:143], v3 offset:39424
	ds_read_b64_tr_b16 v[144:145], v3 offset:34848
	ds_read_b64_tr_b16 v[146:147], v3 offset:39456
	ds_read_b64_tr_b16 v[246:247], v3 offset:34880
	ds_read_b64_tr_b16 v[248:249], v3 offset:39488
	ds_read_b64_tr_b16 v[250:251], v3 offset:34912
	ds_read_b64_tr_b16 v[252:253], v3 offset:39520
	s_waitcnt lgkmcnt(6)
	v_mfma_f32_16x16x32_f16 v[4:7], v[140:143], v[76:79], v[4:7]
	v_mfma_f32_16x16x32_f16 v[108:111], v[140:143], v[100:103], v[124:127]
	ds_read_b64_tr_b16 v[140:141], v3 offset:34944
	ds_read_b64_tr_b16 v[142:143], v3 offset:39552
	s_waitcnt lgkmcnt(6)
	v_mfma_f32_16x16x32_f16 v[120:123], v[144:147], v[100:103], v[120:123]
	v_mfma_f32_16x16x32_f16 v[8:11], v[144:147], v[76:79], v[8:11]
	ds_read_b64_tr_b16 v[144:145], v3 offset:34976
	ds_read_b64_tr_b16 v[146:147], v3 offset:39584
	s_waitcnt lgkmcnt(6)
	v_mfma_f32_16x16x32_f16 v[12:15], v[246:249], v[76:79], v[12:15]
	v_mfma_f32_16x16x32_f16 v[116:119], v[246:249], v[100:103], v[116:119]
	ds_read_b64_tr_b16 v[246:247], v3 offset:35008
	ds_read_b64_tr_b16 v[248:249], v3 offset:39616
	s_waitcnt lgkmcnt(6)
	v_mfma_f32_16x16x32_f16 v[64:67], v[250:253], v[76:79], v[64:67]
	v_mfma_f32_16x16x32_f16 v[112:115], v[250:253], v[100:103], v[112:115]
	ds_read_b64_tr_b16 v[250:251], v3 offset:35040
	ds_read_b64_tr_b16 v[252:253], v3 offset:39648
	s_waitcnt lgkmcnt(6)
	v_mfma_f32_16x16x32_f16 v[60:63], v[140:143], v[76:79], v[60:63]
	v_mfma_f32_16x16x32_f16 v[30:33], v[140:143], v[100:103], v[30:33]
	ds_read_b64_tr_b16 v[140:141], v3 offset:44032
	ds_read_b64_tr_b16 v[142:143], v3 offset:48640
	s_waitcnt lgkmcnt(6)
	v_mfma_f32_16x16x32_f16 v[56:59], v[144:147], v[76:79], v[56:59]
	v_mfma_f32_16x16x32_f16 v[104:107], v[144:147], v[100:103], v[104:107]
	ds_read_b64_tr_b16 v[144:145], v3 offset:44064
	ds_read_b64_tr_b16 v[146:147], v3 offset:48672
	s_waitcnt lgkmcnt(6)
	v_mfma_f32_16x16x32_f16 v[52:55], v[246:249], v[76:79], v[52:55]
	v_mfma_f32_16x16x32_f16 v[22:25], v[246:249], v[100:103], v[22:25]
	ds_read_b64_tr_b16 v[246:247], v3 offset:44096
	ds_read_b64_tr_b16 v[248:249], v3 offset:48704
	s_waitcnt lgkmcnt(6)
	v_mfma_f32_16x16x32_f16 v[128:131], v[250:253], v[76:79], v[68:71]
	v_mfma_f32_16x16x32_f16 v[26:29], v[250:253], v[100:103], v[26:29]
	ds_read_b64_tr_b16 v[250:251], v3 offset:44128
	ds_read_b64_tr_b16 v[252:253], v3 offset:48736
	s_waitcnt lgkmcnt(6)
	v_mfma_f32_16x16x32_f16 v[88:91], v[140:143], v[96:99], v[4:7]
	v_mfma_f32_16x16x32_f16 v[124:127], v[140:143], v[18:21], v[108:111]
	ds_read_b64_tr_b16 v[140:141], v3 offset:44160
	ds_read_b64_tr_b16 v[142:143], v3 offset:48768
	s_waitcnt lgkmcnt(6)
	v_mfma_f32_16x16x32_f16 v[76:79], v[144:147], v[96:99], v[8:11]
	v_mfma_f32_16x16x32_f16 v[120:123], v[144:147], v[18:21], v[120:123]
	ds_read_b64_tr_b16 v[144:145], v3 offset:44192
	ds_read_b64_tr_b16 v[146:147], v3 offset:48800
	s_waitcnt lgkmcnt(6)
	v_mfma_f32_16x16x32_f16 v[68:71], v[246:249], v[96:99], v[12:15]
	v_mfma_f32_16x16x32_f16 v[116:119], v[246:249], v[18:21], v[116:119]
	ds_read_b64_tr_b16 v[246:247], v3 offset:44224
	ds_read_b64_tr_b16 v[248:249], v3 offset:48832
	s_waitcnt lgkmcnt(6)
	v_mfma_f32_16x16x32_f16 v[64:67], v[250:253], v[96:99], v[64:67]
	v_mfma_f32_16x16x32_f16 v[112:115], v[250:253], v[18:21], v[112:115]
	ds_read_b64_tr_b16 v[250:251], v3 offset:44256
	ds_read_b64_tr_b16 v[252:253], v3 offset:48864
	s_waitcnt lgkmcnt(6)
	v_mfma_f32_16x16x32_f16 v[60:63], v[140:143], v[96:99], v[60:63]
	v_mfma_f32_16x16x32_f16 v[108:111], v[140:143], v[18:21], v[30:33]
	s_waitcnt lgkmcnt(4)
	v_mfma_f32_16x16x32_f16 v[56:59], v[144:147], v[96:99], v[56:59]
	v_mfma_f32_16x16x32_f16 v[104:107], v[144:147], v[18:21], v[104:107]
	s_waitcnt lgkmcnt(2)
	v_mfma_f32_16x16x32_f16 v[52:55], v[246:249], v[96:99], v[52:55]
	v_mfma_f32_16x16x32_f16 v[100:103], v[246:249], v[18:21], v[22:25]
	s_waitcnt lgkmcnt(0)
	v_mfma_f32_16x16x32_f16 v[96:99], v[250:253], v[96:99], v[128:131]
	v_mfma_f32_16x16x32_f16 v[128:131], v[250:253], v[18:21], v[26:29]
	s_add_i32 s49, s49, 1
	s_add_i32 s24, s24, 64
	s_add_i32 s2, s31, s49
	v_lshl_add_u64 v[172:173], v[172:173], 0, s[20:21]
	v_lshl_add_u64 v[170:171], v[170:171], 0, s[20:21]
	s_cmp_eq_u32 s2, 2
	v_subrev_u32_e32 v167, 64, v167
	s_barrier
	s_cbranch_scc1 .LBB0_691
	v_mov_b32_e32 v193, v133
	v_mov_b32_e32 v191, v134
	v_mov_b32_e32 v192, v132
	v_mov_b32_e32 v190, v2
	s_branch .LBB0_677
